# GEMM: first K iteration peeled with zero-C MFMAs, the 128 accumulator v_mov zeroing per unit removed
# speedup vs baseline: 1.0137x; 1.0137x over previous
; #define PG8_STAGE(bufoff, gbase, voff) do { _Pragma("unroll") for (int _i = 0; _i < 2; ++_i) \
;         __builtin_amdgcn_global_load_lds((const unsigned*)((const char*)(gbase) + (voff)[_i]), (LAS unsigned*)(lds + (bufoff) + ldsw + _i * 8192), 16, 0, 0); } while (0)
; #define PG8_LDA(dst, b, h) do { _Pragma("unroll") for (int m = 0; m < 4; ++m) _Pragma("unroll") for (int k = 0; k < 2; ++k) dst[m][k] = *(const LAS bf16x8*)(lds + PG8_SA(b, h) + aoff + m * 2048 + k * 1024); } while (0)
; #define PG8_LDB(dst, b, h) do { _Pragma("unroll") for (int n = 0; n < 2; ++n) _Pragma("unroll") for (int k = 0; k < 2; ++k) dst[n][k] = *(const LAS bf16x8*)(lds + PG8_SB(b, h) + boff + n * 2048 + k * 1024); } while (0)
; #define PG8_MMA(ai, bj, At, Bt) do { __builtin_amdgcn_s_setprio(1); _Pragma("unroll") for (int m = 0; m < 4; ++m) _Pragma("unroll") for (int n = 0; n < 2; ++n) _Pragma("unroll") for (int k = 0; k < 2; ++k) \
;         acc[ai][bj][m][n] = __builtin_amdgcn_mfma_f32_16x16x32_bf16(Bt[n][k], At[m][k], acc[ai][bj][m][n], 0, 0, 0); __builtin_amdgcn_s_setprio(0); } while (0)
; #define PG8_BAR __builtin_amdgcn_s_barrier()
; template <class Epi>
; DI void gemm_phase(LAS unsigned char* lds, const Gemm g, const StaticOrder& S, const Epi& E) {
;     ...
;         const bool has_next = S.next(ui + 1, nxt);
;         const char* nA = has_next ? (const char*)g.A + (size_t)nxt.pm * tstepA + PG8_AOFS(nxt) : cA; const char* nB = has_next ? (const char*)g.Bt + (size_t)nxt.pn * tstepB + PG8_BOFS(nxt) : cB;
;         const int ntc = PG8_NT(cur);
;         for (int t = 0; t < ntc; t += 2) {
;             const bool last = (t == ntc - 2);
;             const char* a1 = cA + (size_t)(t + 1) * kstep;
;             const char* a2 = last ? nA : cA + (size_t)(t + 2) * kstep; const char* b2 = last ? nB : cB + (size_t)(t + 2) * kstep;
;             const char* a3 = a2 + kstep; const char* b3 = b2 + kstep;
;             PG8_LDB(B0, 0, 0); PG8_SCHED; PG8_LDA(At, 0, 0); PG8_STAGE(PG8_SA(1, 1), a1 + hstepA, voffA);
;             PG8_WAIT_L(8); PG8_BAR; PG8_WAIT_L(0); PG8_MMA(0, 0, At, B0); PG8_BAR; PG8_SCHED;
;             PG8_LDB(B1, 0, 1); PG8_STAGE(PG8_SB(0, 0), b2, voffB);
;             PG8_BAR; PG8_WAIT_L(0); PG8_MMA(0, 1, At, B1); PG8_BAR;
;             PG8_LDA(At, 0, 1); PG8_STAGE(PG8_SA(0, 0), a2, voffA);
;             PG8_BAR; PG8_WAIT_L(0); PG8_MMA(1, 0, At, B0); PG8_BAR; PG8_SCHED;
.LBB0_240:
	s_cmp_gt_i32 s70, 3
	s_cselect_b64 s[20:21], -1, 0
	s_and_b64 s[20:21], s[94:95], s[20:21]
	s_and_b64 s[20:21], s[20:21], exec
	s_cselect_b32 s11, 4, s86
	s_add_i32 s20, s11, -2
	s_add_u32 s21, s16, 0x100
	s_addc_u32 s44, s17, 0
	s_add_u32 s16, s18, 0x80
	s_addc_u32 s17, s19, 0
	s_mov_b32 s18, 0
	s_add_i32 s45, s18, 2
	s_add_u32 s37, s16, 0x80
	s_addc_u32 s19, s17, 0
	s_waitcnt lgkmcnt(0)
	s_add_i32 s46, 0, 0x10000
	v_add_u32_e32 v0, s46, v147
	ds_read_b128 v[130:133], v0
	ds_read_b128 v[148:151], v0 offset:1024
	ds_read_b128 v[152:155], v0 offset:2048
	ds_read_b128 v[156:159], v0 offset:3072
	s_cmp_eq_u32 s20, s18
	s_cselect_b32 s18, s12, s37
	s_cselect_b32 s19, s13, s19
	s_cselect_b32 s43, s15, s44
	s_cselect_b32 s42, s14, s21
	v_lshl_add_u64 v[204:205], s[16:17], 0, v[144:145]
	s_add_i32 m0, s89, 0xc000
	ds_read_b128 v[160:163], v186
	ds_read_b128 v[164:167], v186 offset:1024
	ds_read_b128 v[168:171], v186 offset:2048
	ds_read_b128 v[172:175], v186 offset:3072
	ds_read_b128 v[188:191], v186 offset:4096
	ds_read_b128 v[192:195], v186 offset:5120
	ds_read_b128 v[196:199], v186 offset:6144
	ds_read_b128 v[200:203], v186 offset:7168
	global_load_lds_dwordx4 v[204:205], off
	v_lshl_add_u64 v[204:205], s[16:17], 0, v[142:143]
	s_add_i32 m0, s89, 0xe000
	s_nop 0
	global_load_lds_dwordx4 v[204:205], off
	s_waitcnt lgkmcnt(8)
	s_barrier
	s_waitcnt lgkmcnt(0)
	s_setprio 1
	s_waitcnt lgkmcnt(0)
	v_mfma_f32_16x16x32_bf16 v[126:129], v[130:133], v[160:163], 0
	v_mfma_f32_16x16x32_bf16 v[122:125], v[152:155], v[160:163], 0
	v_mfma_f32_16x16x32_bf16 v[118:121], v[130:133], v[168:171], 0
	v_mfma_f32_16x16x32_bf16 v[114:117], v[152:155], v[168:171], 0
	v_mfma_f32_16x16x32_bf16 v[106:109], v[130:133], v[188:191], 0
	v_mfma_f32_16x16x32_bf16 v[98:101], v[152:155], v[188:191], 0
	v_mfma_f32_16x16x32_bf16 v[90:93], v[130:133], v[196:199], 0
	v_mfma_f32_16x16x32_bf16 v[82:85], v[152:155], v[196:199], 0
	v_mfma_f32_16x16x32_bf16 v[126:129], v[148:151], v[164:167], v[126:129]
	v_mfma_f32_16x16x32_bf16 v[122:125], v[156:159], v[164:167], v[122:125]
	v_mfma_f32_16x16x32_bf16 v[118:121], v[148:151], v[172:175], v[118:121]
	v_mfma_f32_16x16x32_bf16 v[114:117], v[156:159], v[172:175], v[114:117]
	v_mfma_f32_16x16x32_bf16 v[106:109], v[148:151], v[192:195], v[106:109]
	v_mfma_f32_16x16x32_bf16 v[98:101], v[156:159], v[192:195], v[98:101]
	v_mfma_f32_16x16x32_bf16 v[90:93], v[148:151], v[200:203], v[90:93]
	v_mfma_f32_16x16x32_bf16 v[82:85], v[156:159], v[200:203], v[82:85]
	s_setprio 0
	s_barrier
	s_add_i32 s37, 0, 0x14000
	s_add_i32 s46, s46, s88
	v_add_u32_e32 v0, s37, v147
	v_lshl_add_u64 v[220:221], s[42:43], 0, v[136:137]
	s_mov_b32 m0, s46
	ds_read_b128 v[204:207], v0
	ds_read_b128 v[208:211], v0 offset:1024
	ds_read_b128 v[212:215], v0 offset:2048
	ds_read_b128 v[216:219], v0 offset:3072
	global_load_lds_dwordx4 v[220:221], off
	v_lshl_add_u64 v[222:223], s[42:43], 0, v[140:141]
	s_add_i32 m0, s46, 0x2000
	s_nop 0
	global_load_lds_dwordx4 v[222:223], off
	s_barrier
	s_waitcnt lgkmcnt(0)
	s_setprio 1
	s_waitcnt lgkmcnt(0)
	v_mfma_f32_16x16x32_bf16 v[110:113], v[204:207], v[160:163], 0
	v_mfma_f32_16x16x32_bf16 v[102:105], v[212:215], v[160:163], 0
	v_mfma_f32_16x16x32_bf16 v[94:97], v[204:207], v[168:171], 0
	v_mfma_f32_16x16x32_bf16 v[86:89], v[212:215], v[168:171], 0
	v_mfma_f32_16x16x32_bf16 v[78:81], v[204:207], v[188:191], 0
	v_mfma_f32_16x16x32_bf16 v[74:77], v[212:215], v[188:191], 0
	v_mfma_f32_16x16x32_bf16 v[70:73], v[204:207], v[196:199], 0
	v_mfma_f32_16x16x32_bf16 v[66:69], v[212:215], v[196:199], 0
	v_mfma_f32_16x16x32_bf16 v[110:113], v[208:211], v[164:167], v[110:113]
	v_mfma_f32_16x16x32_bf16 v[102:105], v[216:219], v[164:167], v[102:105]
	v_mfma_f32_16x16x32_bf16 v[94:97], v[208:211], v[172:175], v[94:97]
	v_mfma_f32_16x16x32_bf16 v[86:89], v[216:219], v[172:175], v[86:89]
	v_mfma_f32_16x16x32_bf16 v[78:81], v[208:211], v[192:195], v[78:81]
	v_mfma_f32_16x16x32_bf16 v[74:77], v[216:219], v[192:195], v[74:77]
	v_mfma_f32_16x16x32_bf16 v[70:73], v[208:211], v[200:203], v[70:73]
	v_mfma_f32_16x16x32_bf16 v[66:69], v[216:219], v[200:203], v[66:69]
	s_setprio 0
	s_mov_b32 m0, s89
	v_lshl_add_u64 v[224:225], s[18:19], 0, v[134:135]
	s_barrier
	ds_read_b128 v[160:163], v186 offset:16384
	ds_read_b128 v[164:167], v186 offset:17408
	ds_read_b128 v[168:171], v186 offset:18432
	ds_read_b128 v[172:175], v186 offset:19456
	ds_read_b128 v[188:191], v186 offset:20480
	ds_read_b128 v[192:195], v186 offset:21504
	ds_read_b128 v[196:199], v186 offset:22528
	ds_read_b128 v[200:203], v186 offset:23552
	global_load_lds_dwordx4 v[224:225], off
	v_lshl_add_u64 v[226:227], s[18:19], 0, v[138:139]
	s_mov_b32 m0, s74
	s_nop 0
	global_load_lds_dwordx4 v[226:227], off
	s_barrier
	s_waitcnt lgkmcnt(0)
	s_setprio 1
	s_waitcnt lgkmcnt(0)
	v_mfma_f32_16x16x32_bf16 v[62:65], v[130:133], v[160:163], 0
	v_mfma_f32_16x16x32_bf16 v[58:61], v[152:155], v[160:163], 0
	v_mfma_f32_16x16x32_bf16 v[54:57], v[130:133], v[168:171], 0
	v_mfma_f32_16x16x32_bf16 v[50:53], v[152:155], v[168:171], 0
	v_mfma_f32_16x16x32_bf16 v[46:49], v[130:133], v[188:191], 0
	v_mfma_f32_16x16x32_bf16 v[38:41], v[152:155], v[188:191], 0
	v_mfma_f32_16x16x32_bf16 v[30:33], v[130:133], v[196:199], 0
	v_mfma_f32_16x16x32_bf16 v[22:25], v[152:155], v[196:199], 0
	v_mfma_f32_16x16x32_bf16 v[62:65], v[148:151], v[164:167], v[62:65]
	v_mfma_f32_16x16x32_bf16 v[58:61], v[156:159], v[164:167], v[58:61]
	v_mfma_f32_16x16x32_bf16 v[54:57], v[148:151], v[172:175], v[54:57]
	v_mfma_f32_16x16x32_bf16 v[50:53], v[156:159], v[172:175], v[50:53]
	v_mfma_f32_16x16x32_bf16 v[46:49], v[148:151], v[192:195], v[46:49]
	v_mfma_f32_16x16x32_bf16 v[38:41], v[156:159], v[192:195], v[38:41]
	v_mfma_f32_16x16x32_bf16 v[30:33], v[148:151], v[200:203], v[30:33]
	v_mfma_f32_16x16x32_bf16 v[22:25], v[156:159], v[200:203], v[22:25]
	s_setprio 0
	s_barrier
; #define PG8_STAGE(bufoff, gbase, voff) do { _Pragma("unroll") for (int _i = 0; _i < 2; ++_i) \
;         __builtin_amdgcn_global_load_lds((const unsigned*)((const char*)(gbase) + (voff)[_i]), (LAS unsigned*)(lds + (bufoff) + ldsw + _i * 8192), 16, 0, 0); } while (0)
; #define PG8_LDA(dst, b, h) do { _Pragma("unroll") for (int m = 0; m < 4; ++m) _Pragma("unroll") for (int k = 0; k < 2; ++k) dst[m][k] = *(const LAS bf16x8*)(lds + PG8_SA(b, h) + aoff + m * 2048 + k * 1024); } while (0)
; #define PG8_LDB(dst, b, h) do { _Pragma("unroll") for (int n = 0; n < 2; ++n) _Pragma("unroll") for (int k = 0; k < 2; ++k) dst[n][k] = *(const LAS bf16x8*)(lds + PG8_SB(b, h) + boff + n * 2048 + k * 1024); } while (0)
; #define PG8_MMA(ai, bj, At, Bt) do { __builtin_amdgcn_s_setprio(1); _Pragma("unroll") for (int m = 0; m < 4; ++m) _Pragma("unroll") for (int n = 0; n < 2; ++n) _Pragma("unroll") for (int k = 0; k < 2; ++k) \
;         acc[ai][bj][m][n] = __builtin_amdgcn_mfma_f32_16x16x32_bf16(Bt[n][k], At[m][k], acc[ai][bj][m][n], 0, 0, 0); __builtin_amdgcn_s_setprio(0); } while (0)
; #define PG8_WAIT_V(n) asm volatile("s_waitcnt vmcnt(" #n ")" ::: "memory")
; #define PG8_WAIT_L(n) asm volatile("s_waitcnt lgkmcnt(" #n ")" ::: "memory")
; #define PG8_BAR __builtin_amdgcn_s_barrier()
; #define PG8_SCHED __builtin_amdgcn_sched_barrier(0)
; template <class Epi>
; DI void gemm_phase(LAS unsigned char* lds, const Gemm g, const StaticOrder& S, const Epi& E) {
;     ...
;             PG8_STAGE(PG8_SB(0, 1), b2 + hstepB, voffB);
;             PG8_WAIT_V(6); PG8_BAR; PG8_MMA(1, 1, At, B1); PG8_BAR;
;             PG8_LDB(B0, 1, 0); PG8_SCHED; PG8_LDA(At, 1, 0); PG8_STAGE(PG8_SA(0, 1), a2 + hstepA, voffA);
;             PG8_WAIT_L(8); PG8_BAR; PG8_WAIT_L(0); PG8_MMA(0, 0, At, B0); PG8_BAR; PG8_SCHED;
;             PG8_LDB(B1, 1, 1); PG8_STAGE(PG8_SB(1, 0), b3, voffB);
	s_add_u32 s42, s42, s98
	s_addc_u32 s43, s43, 0
	s_add_i32 s37, s37, s88
	v_lshl_add_u64 v[228:229], s[42:43], 0, v[136:137]
	s_mov_b32 m0, s37
	v_lshl_add_u64 v[230:231], s[42:43], 0, v[140:141]
	global_load_lds_dwordx4 v[228:229], off
	s_add_i32 m0, s37, 0x2000
	s_nop 0
	global_load_lds_dwordx4 v[230:231], off
	s_waitcnt vmcnt(6)
	s_barrier
	s_setprio 1
	v_mfma_f32_16x16x32_bf16 v[42:45], v[204:207], v[160:163], 0
	v_mfma_f32_16x16x32_bf16 v[34:37], v[212:215], v[160:163], 0
	v_mfma_f32_16x16x32_bf16 v[26:29], v[204:207], v[168:171], 0
	v_mfma_f32_16x16x32_bf16 v[18:21], v[212:215], v[168:171], 0
	v_mfma_f32_16x16x32_bf16 v[14:17], v[204:207], v[188:191], 0
	v_mfma_f32_16x16x32_bf16 v[10:13], v[212:215], v[188:191], 0
	v_mfma_f32_16x16x32_bf16 v[6:9], v[204:207], v[196:199], 0
	v_mfma_f32_16x16x32_bf16 v[2:5], v[212:215], v[196:199], 0
	v_mfma_f32_16x16x32_bf16 v[42:45], v[208:211], v[164:167], v[42:45]
	v_mfma_f32_16x16x32_bf16 v[34:37], v[216:219], v[164:167], v[34:37]
	v_mfma_f32_16x16x32_bf16 v[26:29], v[208:211], v[172:175], v[26:29]
	v_mfma_f32_16x16x32_bf16 v[18:21], v[216:219], v[172:175], v[18:21]
	v_mfma_f32_16x16x32_bf16 v[14:17], v[208:211], v[192:195], v[14:17]
	v_mfma_f32_16x16x32_bf16 v[10:13], v[216:219], v[192:195], v[10:13]
	v_mfma_f32_16x16x32_bf16 v[6:9], v[208:211], v[200:203], v[6:9]
	v_mfma_f32_16x16x32_bf16 v[2:5], v[216:219], v[200:203], v[2:5]
	s_setprio 0
	s_add_i32 s37, 0, 0x18000
	v_add_u32_e32 v0, s37, v147
	s_barrier
	ds_read_b128 v[130:133], v0
	ds_read_b128 v[148:151], v0 offset:1024
	ds_read_b128 v[152:155], v0 offset:2048
	ds_read_b128 v[156:159], v0 offset:3072
	s_add_u32 s18, s18, s72
	s_addc_u32 s19, s19, 0
	s_mov_b32 m0, s75
	v_lshl_add_u64 v[204:205], s[18:19], 0, v[134:135]
	ds_read_b128 v[160:163], v186 offset:32768
	ds_read_b128 v[164:167], v186 offset:33792
	ds_read_b128 v[168:171], v186 offset:34816
	ds_read_b128 v[172:175], v186 offset:35840
	ds_read_b128 v[188:191], v186 offset:36864
	ds_read_b128 v[192:195], v186 offset:37888
	ds_read_b128 v[196:199], v186 offset:38912
	ds_read_b128 v[200:203], v186 offset:39936
	global_load_lds_dwordx4 v[204:205], off
	v_lshl_add_u64 v[204:205], s[18:19], 0, v[138:139]
	s_mov_b32 m0, s3
	s_nop 0
	global_load_lds_dwordx4 v[204:205], off
	s_waitcnt lgkmcnt(8)
	s_barrier
	s_waitcnt lgkmcnt(0)
	s_setprio 1
	s_waitcnt lgkmcnt(0)
	v_mfma_f32_16x16x32_bf16 v[126:129], v[130:133], v[160:163], v[126:129]
	v_mfma_f32_16x16x32_bf16 v[122:125], v[152:155], v[160:163], v[122:125]
	v_mfma_f32_16x16x32_bf16 v[118:121], v[130:133], v[168:171], v[118:121]
	v_mfma_f32_16x16x32_bf16 v[114:117], v[152:155], v[168:171], v[114:117]
	v_mfma_f32_16x16x32_bf16 v[106:109], v[130:133], v[188:191], v[106:109]
	v_mfma_f32_16x16x32_bf16 v[98:101], v[152:155], v[188:191], v[98:101]
	v_mfma_f32_16x16x32_bf16 v[90:93], v[130:133], v[196:199], v[90:93]
	v_mfma_f32_16x16x32_bf16 v[82:85], v[152:155], v[196:199], v[82:85]
	v_mfma_f32_16x16x32_bf16 v[126:129], v[148:151], v[164:167], v[126:129]
	v_mfma_f32_16x16x32_bf16 v[122:125], v[156:159], v[164:167], v[122:125]
	v_mfma_f32_16x16x32_bf16 v[118:121], v[148:151], v[172:175], v[118:121]
	v_mfma_f32_16x16x32_bf16 v[114:117], v[156:159], v[172:175], v[114:117]
	v_mfma_f32_16x16x32_bf16 v[106:109], v[148:151], v[192:195], v[106:109]
	v_mfma_f32_16x16x32_bf16 v[98:101], v[156:159], v[192:195], v[98:101]
	v_mfma_f32_16x16x32_bf16 v[90:93], v[148:151], v[200:203], v[90:93]
	v_mfma_f32_16x16x32_bf16 v[82:85], v[156:159], v[200:203], v[82:85]
	s_setprio 0
	s_barrier
	s_add_i32 s18, 0, 0x1c000
	s_add_i32 s19, s37, s88
	v_add_u32_e32 v0, s18, v147
	v_lshl_add_u64 v[220:221], v[220:221], 0, s[82:83]
	s_mov_b32 m0, s19
	ds_read_b128 v[204:207], v0
	ds_read_b128 v[208:211], v0 offset:1024
	ds_read_b128 v[212:215], v0 offset:2048
	ds_read_b128 v[216:219], v0 offset:3072
	global_load_lds_dwordx4 v[220:221], off
	v_lshl_add_u64 v[220:221], v[222:223], 0, s[82:83]
	s_add_i32 m0, s19, 0x2000
	s_nop 0
	global_load_lds_dwordx4 v[220:221], off
	s_barrier
; #define PG8_STAGE(bufoff, gbase, voff) do { _Pragma("unroll") for (int _i = 0; _i < 2; ++_i) \
;         __builtin_amdgcn_global_load_lds((const unsigned*)((const char*)(gbase) + (voff)[_i]), (LAS unsigned*)(lds + (bufoff) + ldsw + _i * 8192), 16, 0, 0); } while (0)
; #define PG8_LDA(dst, b, h) do { _Pragma("unroll") for (int m = 0; m < 4; ++m) _Pragma("unroll") for (int k = 0; k < 2; ++k) dst[m][k] = *(const LAS bf16x8*)(lds + PG8_SA(b, h) + aoff + m * 2048 + k * 1024); } while (0)
; #define PG8_MMA(ai, bj, At, Bt) do { __builtin_amdgcn_s_setprio(1); _Pragma("unroll") for (int m = 0; m < 4; ++m) _Pragma("unroll") for (int n = 0; n < 2; ++n) _Pragma("unroll") for (int k = 0; k < 2; ++k) \
;         acc[ai][bj][m][n] = __builtin_amdgcn_mfma_f32_16x16x32_bf16(Bt[n][k], At[m][k], acc[ai][bj][m][n], 0, 0, 0); __builtin_amdgcn_s_setprio(0); } while (0)
; #define PG8_WAIT_V(n) asm volatile("s_waitcnt vmcnt(" #n ")" ::: "memory")
; #define PG8_WAIT_L(n) asm volatile("s_waitcnt lgkmcnt(" #n ")" ::: "memory")
; #define PG8_BAR __builtin_amdgcn_s_barrier()
; #define PG8_SCHED __builtin_amdgcn_sched_barrier(0)
; template <class Epi>
; DI void gemm_phase(LAS unsigned char* lds, const Gemm g, const StaticOrder& S, const Epi& E) {
;     ...
;             PG8_BAR; PG8_WAIT_L(0); PG8_MMA(0, 1, At, B1); PG8_BAR;
;             PG8_LDA(At, 1, 1); PG8_STAGE(PG8_SA(1, 0), a3, voffA);
;             PG8_BAR; PG8_WAIT_L(0); PG8_MMA(1, 0, At, B0); PG8_BAR; PG8_SCHED;
;             PG8_STAGE(PG8_SB(1, 1), b3 + hstepB, voffB);
;             PG8_WAIT_V(6); PG8_BAR; PG8_MMA(1, 1, At, B1); PG8_BAR;
;         }
	s_waitcnt lgkmcnt(0)
	s_setprio 1
	s_waitcnt lgkmcnt(0)
	v_mfma_f32_16x16x32_bf16 v[110:113], v[204:207], v[160:163], v[110:113]
	v_mfma_f32_16x16x32_bf16 v[102:105], v[212:215], v[160:163], v[102:105]
	v_mfma_f32_16x16x32_bf16 v[94:97], v[204:207], v[168:171], v[94:97]
	v_mfma_f32_16x16x32_bf16 v[86:89], v[212:215], v[168:171], v[86:89]
	v_mfma_f32_16x16x32_bf16 v[78:81], v[204:207], v[188:191], v[78:81]
	v_mfma_f32_16x16x32_bf16 v[74:77], v[212:215], v[188:191], v[74:77]
	v_mfma_f32_16x16x32_bf16 v[70:73], v[204:207], v[196:199], v[70:73]
	v_mfma_f32_16x16x32_bf16 v[66:69], v[212:215], v[196:199], v[66:69]
	v_mfma_f32_16x16x32_bf16 v[110:113], v[208:211], v[164:167], v[110:113]
	v_mfma_f32_16x16x32_bf16 v[102:105], v[216:219], v[164:167], v[102:105]
	v_mfma_f32_16x16x32_bf16 v[94:97], v[208:211], v[172:175], v[94:97]
	v_mfma_f32_16x16x32_bf16 v[86:89], v[216:219], v[172:175], v[86:89]
	v_mfma_f32_16x16x32_bf16 v[78:81], v[208:211], v[192:195], v[78:81]
	v_mfma_f32_16x16x32_bf16 v[74:77], v[216:219], v[192:195], v[74:77]
	v_mfma_f32_16x16x32_bf16 v[70:73], v[208:211], v[200:203], v[70:73]
	v_mfma_f32_16x16x32_bf16 v[66:69], v[216:219], v[200:203], v[66:69]
	s_setprio 0
	s_mov_b32 m0, s24
	v_lshl_add_u64 v[220:221], v[224:225], 0, s[82:83]
	s_barrier
	ds_read_b128 v[160:163], v186 offset:49152
	ds_read_b128 v[164:167], v186 offset:50176
	ds_read_b128 v[168:171], v186 offset:51200
	ds_read_b128 v[172:175], v186 offset:52224
	ds_read_b128 v[188:191], v186 offset:53248
	ds_read_b128 v[192:195], v186 offset:54272
	ds_read_b128 v[196:199], v186 offset:55296
	ds_read_b128 v[200:203], v186 offset:56320
	global_load_lds_dwordx4 v[220:221], off
	v_lshl_add_u64 v[220:221], v[226:227], 0, s[82:83]
	s_mov_b32 m0, s97
	s_nop 0
	global_load_lds_dwordx4 v[220:221], off
	s_barrier
	s_waitcnt lgkmcnt(0)
	s_setprio 1
	s_waitcnt lgkmcnt(0)
	v_mfma_f32_16x16x32_bf16 v[62:65], v[130:133], v[160:163], v[62:65]
	v_mfma_f32_16x16x32_bf16 v[58:61], v[152:155], v[160:163], v[58:61]
	v_mfma_f32_16x16x32_bf16 v[54:57], v[130:133], v[168:171], v[54:57]
	v_mfma_f32_16x16x32_bf16 v[50:53], v[152:155], v[168:171], v[50:53]
	v_mfma_f32_16x16x32_bf16 v[46:49], v[130:133], v[188:191], v[46:49]
	v_mfma_f32_16x16x32_bf16 v[38:41], v[152:155], v[188:191], v[38:41]
	v_mfma_f32_16x16x32_bf16 v[30:33], v[130:133], v[196:199], v[30:33]
	v_mfma_f32_16x16x32_bf16 v[22:25], v[152:155], v[196:199], v[22:25]
	v_mfma_f32_16x16x32_bf16 v[62:65], v[148:151], v[164:167], v[62:65]
	v_mfma_f32_16x16x32_bf16 v[58:61], v[156:159], v[164:167], v[58:61]
	v_mfma_f32_16x16x32_bf16 v[54:57], v[148:151], v[172:175], v[54:57]
	v_mfma_f32_16x16x32_bf16 v[50:53], v[156:159], v[172:175], v[50:53]
	v_mfma_f32_16x16x32_bf16 v[46:49], v[148:151], v[192:195], v[46:49]
	v_mfma_f32_16x16x32_bf16 v[38:41], v[156:159], v[192:195], v[38:41]
	v_mfma_f32_16x16x32_bf16 v[30:33], v[148:151], v[200:203], v[30:33]
	v_mfma_f32_16x16x32_bf16 v[22:25], v[156:159], v[200:203], v[22:25]
	s_setprio 0
	s_barrier
	s_add_i32 s18, s18, s88
	v_lshl_add_u64 v[130:131], v[228:229], 0, s[82:83]
	s_mov_b32 m0, s18
	s_nop 0
	global_load_lds_dwordx4 v[130:131], off
	v_lshl_add_u64 v[130:131], v[230:231], 0, s[82:83]
	s_add_i32 m0, s18, 0x2000
	s_nop 0
	global_load_lds_dwordx4 v[130:131], off
	s_waitcnt vmcnt(6)
	s_barrier
	s_setprio 1
	v_mfma_f32_16x16x32_bf16 v[42:45], v[204:207], v[160:163], v[42:45]
	v_mfma_f32_16x16x32_bf16 v[34:37], v[212:215], v[160:163], v[34:37]
	v_mfma_f32_16x16x32_bf16 v[26:29], v[204:207], v[168:171], v[26:29]
	v_mfma_f32_16x16x32_bf16 v[18:21], v[212:215], v[168:171], v[18:21]
	v_mfma_f32_16x16x32_bf16 v[14:17], v[204:207], v[188:191], v[14:17]
	v_mfma_f32_16x16x32_bf16 v[10:13], v[212:215], v[188:191], v[10:13]
	v_mfma_f32_16x16x32_bf16 v[6:9], v[204:207], v[196:199], v[6:9]
	v_mfma_f32_16x16x32_bf16 v[2:5], v[212:215], v[196:199], v[2:5]
	v_mfma_f32_16x16x32_bf16 v[42:45], v[208:211], v[164:167], v[42:45]
	v_mfma_f32_16x16x32_bf16 v[34:37], v[216:219], v[164:167], v[34:37]
	v_mfma_f32_16x16x32_bf16 v[26:29], v[208:211], v[172:175], v[26:29]
	v_mfma_f32_16x16x32_bf16 v[18:21], v[216:219], v[172:175], v[18:21]
	v_mfma_f32_16x16x32_bf16 v[14:17], v[208:211], v[192:195], v[14:17]
	v_mfma_f32_16x16x32_bf16 v[10:13], v[216:219], v[192:195], v[10:13]
	v_mfma_f32_16x16x32_bf16 v[6:9], v[208:211], v[200:203], v[6:9]
	v_mfma_f32_16x16x32_bf16 v[2:5], v[216:219], v[200:203], v[2:5]
	s_setprio 0
	s_add_u32 s21, s21, 0x100
	s_addc_u32 s44, s44, 0
	s_add_u32 s16, s16, 0x100
	s_addc_u32 s17, s17, 0
	s_cmp_ge_u32 s45, s11
	s_mov_b32 s18, s45
	s_barrier
	s_cbranch_scc1 .Lk_loop_exit

; DI int otid() { int t = threadIdx.x; asm volatile("" : "+v"(t)); return t; }
; template <class Epi>
; DI void gemm_phase(LAS unsigned char* lds, const Gemm g, const StaticOrder& S, const Epi& E) {
;     ...
;         {
;             int wr2 = wr, wc2 = wc; Unit cu2 = cur; Epi E2 = E;
;             asm volatile("" : "+s"(wr2), "+s"(wc2), "+s"(cu2.pm), "+s"(cu2.pn), "+s"(E2.ws), "+s"(E2.aux));
;             const int ln2 = otid() & 63;
;             const int fr2 = ln2 & 15, fq2 = ln2 >> 4;
;             E2(acc, cu2, wr2, wc2, fr2, fq2, lds);
.Lk_loop_exit:
	s_mov_b64 s[18:19], s[84:85]
	s_mov_b32 s60, s81
	v_readlane_b32 s62, v255, 2
	s_mov_b32 s61, s96
	v_mov_b32_e32 v0, v176
	s_cmp_lt_i32 s29, 2
	s_mov_b64 s[20:21], -1
	s_cbranch_scc1 .LBB0_248
	s_cmp_gt_i32 s29, 2
	s_cbranch_scc0 .LBB0_245
	s_add_u32 s16, s18, 0xb0e2000
	s_addc_u32 s17, s19, 0
	s_mov_b64 s[20:21], 0
